# KV-projection GEMM K-loop: first half-step LDS-DMA issues woven into the MFMA stream (same def-use checked reorder as the other six K-loops)
# speedup vs baseline: 1.0027x; 1.0027x over previous
.LBB0_205:
	s_mul_i32 s17, s16, 0x6000
	v_add_u32_e32 v145, s17, v144
	v_add_u32_e32 v146, s17, v142
	v_add_u32_e32 v198, v145, v140
	v_add_u32_e32 v145, v145, v141
	v_add_u32_e32 v199, v146, v140
	v_add_u32_e32 v200, v146, v141
	s_waitcnt vmcnt(6)
	s_barrier
	ds_read_b128 v[146:149], v198
	ds_read_b128 v[150:153], v198 offset:2048
	ds_read_b128 v[154:157], v199
	ds_read_b128 v[158:161], v199 offset:2048
	ds_read_b128 v[162:165], v199 offset:4096
	ds_read_b128 v[170:173], v199 offset:6144
	ds_read_b128 v[174:177], v145
	ds_read_b128 v[178:181], v145 offset:2048
	ds_read_b128 v[182:185], v200
	ds_read_b128 v[186:189], v200 offset:2048
	ds_read_b128 v[190:193], v200 offset:4096
	ds_read_b128 v[194:197], v200 offset:6144
	s_waitcnt lgkmcnt(0)
	v_mfma_f32_32x32x16_bf16 v[114:129], v[146:149], v[154:157], v[114:129]
	s_waitcnt vmcnt(0)
	s_barrier
	v_mfma_f32_32x32x16_bf16 v[82:97], v[146:149], v[158:161], v[82:97]
	v_mfma_f32_32x32x16_bf16 v[50:65], v[146:149], v[162:165], v[50:65]
	v_mfma_f32_32x32x16_bf16 v[18:33], v[146:149], v[170:173], v[18:33]
	s_add_i32 s18, s17, 0xffffa000
	s_cmp_gt_i32 s16, 0
	s_cselect_b32 s18, s18, 0xc000
	v_add_u32_e32 v145, s18, v0
	v_lshl_add_u64 v[134:135], v[132:133], 0, s[0:1]
	s_mov_b64 s[18:19], 0x1a140000
	v_lshl_add_u64 v[136:137], v[134:135], 0, s[18:19]
	v_readfirstlane_b32 s18, v145
	s_mov_b32 m0, s18
	s_mov_b64 s[18:19], 0x1a141000
	v_add_u32_e32 v146, 0x1000, v145
	global_load_lds_dwordx4 v[136:137], off
	v_mfma_f32_32x32x16_bf16 v[98:113], v[150:153], v[154:157], v[98:113]
	v_lshl_add_u64 v[136:137], v[134:135], 0, s[18:19]
	v_readfirstlane_b32 s18, v146
	s_mov_b32 m0, s18
	s_mov_b64 s[18:19], 0x1a142000
	v_add_u32_e32 v146, 0x2000, v145
	global_load_lds_dwordx4 v[136:137], off
	v_mfma_f32_32x32x16_bf16 v[66:81], v[150:153], v[158:161], v[66:81]
	v_lshl_add_u64 v[136:137], v[134:135], 0, s[18:19]
	v_readfirstlane_b32 s18, v146
	s_mov_b32 m0, s18
	s_mov_b64 s[18:19], 0x1a143000
	v_add_u32_e32 v146, 0x3000, v145
	global_load_lds_dwordx4 v[136:137], off
	v_mfma_f32_32x32x16_bf16 v[34:49], v[150:153], v[162:165], v[34:49]
	v_lshl_add_u64 v[136:137], v[134:135], 0, s[18:19]
	v_readfirstlane_b32 s18, v146
	s_mov_b32 m0, s18
	s_mov_b64 s[18:19], 0xb40000
	global_load_lds_dwordx4 v[136:137], off
	v_mfma_f32_32x32x16_bf16 v[2:17], v[150:153], v[170:173], v[2:17]
	v_lshl_add_u64 v[136:137], v[130:131], 0, s[0:1]
	v_add_u32_e32 v148, 0x4000, v145
	v_lshl_add_u64 v[146:147], v[136:137], 0, s[18:19]
	v_readfirstlane_b32 s18, v148
	s_mov_b32 m0, s18
	s_mov_b64 s[18:19], 0xb41000
	v_add_u32_e32 v145, 0x5000, v145
	global_load_lds_dwordx4 v[146:147], off
	v_mfma_f32_32x32x16_bf16 v[114:129], v[174:177], v[182:185], v[114:129]
	v_lshl_add_u64 v[146:147], v[136:137], 0, s[18:19]
	v_readfirstlane_b32 s18, v145
	s_mov_b32 m0, s18
	s_nop 0
	global_load_lds_dwordx4 v[146:147], off
	v_mfma_f32_32x32x16_bf16 v[98:113], v[178:181], v[182:185], v[98:113]
	s_add_i32 s17, s16, 1
	s_cmp_lg_u32 s16, 2
	s_cselect_b32 s16, s17, 0
	s_mul_i32 s17, s16, 0x6000
	s_add_i32 s18, s17, 0xffffa000
	s_cmp_gt_i32 s16, 0
	s_cselect_b32 s18, s18, 0xc000
	v_add_u32_e32 v145, s18, v0
	s_mov_b64 s[18:19], 0x1a160000
	v_lshl_add_u64 v[146:147], v[134:135], 0, s[18:19]
	v_readfirstlane_b32 s18, v145
	s_mov_b32 m0, s18
	s_mov_b64 s[18:19], 0x1a161000
	v_add_u32_e32 v148, 0x1000, v145
	global_load_lds_dwordx4 v[146:147], off
	v_mfma_f32_32x32x16_bf16 v[82:97], v[174:177], v[186:189], v[82:97]
	v_lshl_add_u64 v[146:147], v[134:135], 0, s[18:19]
	v_readfirstlane_b32 s18, v148
	s_mov_b32 m0, s18
	s_mov_b64 s[18:19], 0x1a162000
	v_add_u32_e32 v148, 0x2000, v145
	global_load_lds_dwordx4 v[146:147], off
	v_mfma_f32_32x32x16_bf16 v[66:81], v[178:181], v[186:189], v[66:81]
	v_lshl_add_u64 v[146:147], v[134:135], 0, s[18:19]
	v_readfirstlane_b32 s18, v148
	s_mov_b32 m0, s18
	s_mov_b64 s[18:19], 0x1a163000
	global_load_lds_dwordx4 v[146:147], off
	v_mfma_f32_32x32x16_bf16 v[50:65], v[174:177], v[190:193], v[50:65]
	v_add_u32_e32 v146, 0x3000, v145
	v_lshl_add_u64 v[134:135], v[134:135], 0, s[18:19]
	v_readfirstlane_b32 s18, v146
	s_mov_b32 m0, s18
	s_mov_b64 s[18:19], 0xb60000
	v_add_u32_e32 v146, 0x4000, v145
	global_load_lds_dwordx4 v[134:135], off
	v_mfma_f32_32x32x16_bf16 v[34:49], v[178:181], v[190:193], v[34:49]
	v_lshl_add_u64 v[134:135], v[136:137], 0, s[18:19]
	v_readfirstlane_b32 s18, v146
	s_mov_b32 m0, s18
	s_mov_b64 s[18:19], 0xb61000
	global_load_lds_dwordx4 v[134:135], off
	v_mfma_f32_32x32x16_bf16 v[18:33], v[174:177], v[194:197], v[18:33]
	v_lshl_add_u64 v[134:135], v[136:137], 0, s[18:19]
	v_add_u32_e32 v136, 0x5000, v145
	s_nop 0
	v_readfirstlane_b32 s18, v136
	s_mov_b32 m0, s18
	s_nop 0
	global_load_lds_dwordx4 v[134:135], off
	v_mfma_f32_32x32x16_bf16 v[2:17], v[178:181], v[194:197], v[2:17]
	v_add_u32_e32 v134, s17, v144
	v_add_u32_e32 v135, s17, v142
	v_add_u32_e32 v145, v134, v140
	s_add_i32 s17, s16, 1
	s_cmp_lg_u32 s16, 2
	s_cselect_b32 s16, s17, 0
	s_add_u32 s0, s0, 0x40000
	s_addc_u32 s1, s1, 0
	s_cmp_eq_u32 s0, 0x3c0000
	v_add_u32_e32 v194, v135, v140
	v_add_u32_e32 v195, v134, v141
	v_add_u32_e32 v196, v135, v141
	ds_read_b128 v[134:137], v145
	ds_read_b128 v[146:149], v145 offset:2048
	ds_read_b128 v[150:153], v194
	ds_read_b128 v[154:157], v194 offset:2048
	ds_read_b128 v[158:161], v194 offset:4096
	ds_read_b128 v[162:165], v194 offset:6144
	ds_read_b128 v[170:173], v195
	ds_read_b128 v[174:177], v195 offset:2048
	ds_read_b128 v[178:181], v196
	ds_read_b128 v[182:185], v196 offset:2048
	ds_read_b128 v[186:189], v196 offset:4096
	ds_read_b128 v[190:193], v196 offset:6144
	s_waitcnt lgkmcnt(0)
	s_nop 0
	v_mfma_f32_32x32x16_bf16 v[114:129], v[134:137], v[150:153], v[114:129]
	v_mfma_f32_32x32x16_bf16 v[98:113], v[146:149], v[150:153], v[98:113]
	v_mfma_f32_32x32x16_bf16 v[82:97], v[134:137], v[154:157], v[82:97]
	v_mfma_f32_32x32x16_bf16 v[66:81], v[146:149], v[154:157], v[66:81]
	v_mfma_f32_32x32x16_bf16 v[50:65], v[134:137], v[158:161], v[50:65]
	v_mfma_f32_32x32x16_bf16 v[34:49], v[146:149], v[158:161], v[34:49]
	v_mfma_f32_32x32x16_bf16 v[18:33], v[134:137], v[162:165], v[18:33]
	v_mfma_f32_32x32x16_bf16 v[2:17], v[146:149], v[162:165], v[2:17]
	v_mfma_f32_32x32x16_bf16 v[114:129], v[170:173], v[178:181], v[114:129]
	v_mfma_f32_32x32x16_bf16 v[98:113], v[174:177], v[178:181], v[98:113]
	v_mfma_f32_32x32x16_bf16 v[82:97], v[170:173], v[182:185], v[82:97]
	v_mfma_f32_32x32x16_bf16 v[66:81], v[174:177], v[182:185], v[66:81]
	v_mfma_f32_32x32x16_bf16 v[50:65], v[170:173], v[186:189], v[50:65]
	v_mfma_f32_32x32x16_bf16 v[34:49], v[174:177], v[186:189], v[34:49]
	v_mfma_f32_32x32x16_bf16 v[18:33], v[170:173], v[190:193], v[18:33]
	v_mfma_f32_32x32x16_bf16 v[2:17], v[174:177], v[190:193], v[2:17]
	s_cbranch_scc0 .LBB0_205
	s_mul_i32 s0, s16, 0x6000
	v_add_u32_e32 v130, s0, v144
	v_add_u32_e32 v131, s0, v142
	s_waitcnt vmcnt(6)
	s_barrier
	v_add_u32_e32 v164, v130, v140
	v_add_u32_e32 v165, v131, v140
	v_add_u32_e32 v190, v130, v141
	v_add_u32_e32 v191, v131, v141
	ds_read_b128 v[130:133], v164
	ds_read_b128 v[134:137], v164 offset:2048
	ds_read_b128 v[144:147], v165
	ds_read_b128 v[148:151], v165 offset:2048
	ds_read_b128 v[152:155], v165 offset:4096
	ds_read_b128 v[156:159], v165 offset:6144
	ds_read_b128 v[160:163], v190
	ds_read_b128 v[170:173], v190 offset:2048
	ds_read_b128 v[174:177], v191
	ds_read_b128 v[178:181], v191 offset:2048
	ds_read_b128 v[182:185], v191 offset:4096
	ds_read_b128 v[186:189], v191 offset:6144
	s_waitcnt lgkmcnt(0)
	s_waitcnt vmcnt(0)
	s_barrier
	v_mfma_f32_32x32x16_bf16 v[50:65], v[130:133], v[152:155], v[50:65]
	v_and_b32_e32 v0, 0xf0, v0
	v_mfma_f32_32x32x16_bf16 v[34:49], v[134:137], v[152:155], v[34:49]
	v_mfma_f32_32x32x16_bf16 v[82:97], v[130:133], v[148:151], v[82:97]
	v_mfma_f32_32x32x16_bf16 v[66:81], v[134:137], v[148:151], v[66:81]
	v_mfma_f32_32x32x16_bf16 v[2:17], v[134:137], v[156:159], v[2:17]
	v_mfma_f32_32x32x16_bf16 v[114:129], v[130:133], v[144:147], v[114:129]
	v_mfma_f32_32x32x16_bf16 v[98:113], v[134:137], v[144:147], v[98:113]
	v_mfma_f32_32x32x16_bf16 v[18:33], v[130:133], v[156:159], v[18:33]
	v_or_b32_e32 v130, 0xa000, v143
	v_add_u32_e32 v131, 0x6000, v142
	v_add_u32_e32 v164, v130, v140
	v_add_u32_e32 v165, v131, v140
	v_mfma_f32_32x32x16_bf16 v[50:65], v[160:163], v[182:185], v[50:65]
	v_mfma_f32_32x32x16_bf16 v[34:49], v[170:173], v[182:185], v[34:49]
	v_mfma_f32_32x32x16_bf16 v[82:97], v[160:163], v[178:181], v[82:97]
	v_mfma_f32_32x32x16_bf16 v[66:81], v[170:173], v[178:181], v[66:81]
	v_mfma_f32_32x32x16_bf16 v[2:17], v[170:173], v[186:189], v[2:17]
	v_mfma_f32_32x32x16_bf16 v[114:129], v[160:163], v[174:177], v[114:129]
	v_mfma_f32_32x32x16_bf16 v[98:113], v[170:173], v[174:177], v[98:113]
	v_mfma_f32_32x32x16_bf16 v[18:33], v[160:163], v[186:189], v[18:33]
	v_add_u32_e32 v186, v130, v141
	v_add_u32_e32 v187, v131, v141
	ds_read_b128 v[130:133], v164
	ds_read_b128 v[134:137], v164 offset:2048
	ds_read_b128 v[140:143], v165
	ds_read_b128 v[144:147], v165 offset:2048
	ds_read_b128 v[148:151], v165 offset:4096
	ds_read_b128 v[152:155], v165 offset:6144
	ds_read_b128 v[156:159], v186
	ds_read_b128 v[160:163], v186 offset:2048
	ds_read_b128 v[170:173], v187
	ds_read_b128 v[174:177], v187 offset:2048
	ds_read_b128 v[178:181], v187 offset:4096
	ds_read_b128 v[182:185], v187 offset:6144
	s_waitcnt lgkmcnt(0)
	s_waitcnt vmcnt(0) lgkmcnt(0)
	s_barrier
	v_mfma_f32_32x32x16_bf16 v[50:65], v[130:133], v[148:151], v[50:65]
	v_mfma_f32_32x32x16_bf16 v[34:49], v[134:137], v[148:151], v[34:49]
	v_mfma_f32_32x32x16_bf16 v[82:97], v[130:133], v[144:147], v[82:97]
	v_mfma_f32_32x32x16_bf16 v[66:81], v[134:137], v[144:147], v[66:81]
	v_mfma_f32_32x32x16_bf16 v[2:17], v[134:137], v[152:155], v[2:17]
	v_mfma_f32_32x32x16_bf16 v[114:129], v[130:133], v[140:143], v[114:129]
	v_mfma_f32_32x32x16_bf16 v[98:113], v[134:137], v[140:143], v[98:113]
	v_lshlrev_b32_e32 v140, 1, v138
	v_and_b32_e32 v140, 0x80, v140
	v_and_b32_e32 v141, 0xfffff9f, v138
	v_lshl_or_b32 v140, v139, 3, v140
	v_mad_u64_u32 v[142:143], s[0:1], v141, s3, v[140:141]
	v_mfma_f32_32x32x16_bf16 v[18:33], v[130:133], v[152:155], v[18:33]
	v_mfma_f32_32x32x16_bf16 v[50:65], v[156:159], v[178:181], v[50:65]
	v_mfma_f32_32x32x16_bf16 v[34:49], v[160:163], v[178:181], v[34:49]
	s_nop 10
	v_cvt_pk_bf16_f32 v50, v50, v51
	v_cvt_pk_bf16_f32 v51, v52, v53
	v_cvt_pk_bf16_f32 v52, v54, v55
	v_add_u32_e32 v54, 0x4000, v142
	v_cvt_pk_bf16_f32 v53, v56, v57
	ds_write2_b64 v54, v[50:51], v[52:53] offset0:128 offset1:130
	v_cvt_pk_bf16_f32 v50, v58, v59
	v_mfma_f32_32x32x16_bf16 v[82:97], v[156:159], v[174:177], v[82:97]
	v_cvt_pk_bf16_f32 v34, v34, v35
	v_cvt_pk_bf16_f32 v35, v36, v37
	v_cvt_pk_bf16_f32 v36, v38, v39
	v_cvt_pk_bf16_f32 v37, v40, v41
	ds_write2_b64 v54, v[34:35], v[36:37] offset0:136 offset1:138
	v_cvt_pk_bf16_f32 v34, v42, v43
	v_cvt_pk_bf16_f32 v35, v44, v45
	v_mfma_f32_32x32x16_bf16 v[66:81], v[160:163], v[174:177], v[66:81]
	v_cvt_pk_bf16_f32 v36, v46, v47
	v_cvt_pk_bf16_f32 v37, v48, v49
	ds_write2_b64 v54, v[34:35], v[36:37] offset0:140 offset1:142
	v_or_b32_e32 v34, 0x60, v138
	v_mad_u64_u32 v[34:35], s[0:1], v34, s3, v[140:141]
	s_lshl_b32 s0, s7, 1
	v_mfma_f32_32x32x16_bf16 v[2:17], v[160:163], v[182:185], v[2:17]
	v_cvt_pk_bf16_f32 v82, v82, v83
	v_cvt_pk_bf16_f32 v83, v84, v85
	v_cvt_pk_bf16_f32 v84, v86, v87
	v_add_u32_e32 v86, 0x2000, v142
	s_nop 0
	v_cvt_pk_bf16_f32 v66, v66, v67
	v_cvt_pk_bf16_f32 v67, v68, v69
	v_cvt_pk_bf16_f32 v68, v70, v71
	v_mfma_f32_32x32x16_bf16 v[114:129], v[156:159], v[170:173], v[114:129]
	v_cvt_pk_bf16_f32 v69, v72, v73
	s_nop 1
	v_cvt_pk_bf16_f32 v2, v2, v3
	v_cvt_pk_bf16_f32 v3, v4, v5
	v_cvt_pk_bf16_f32 v4, v6, v7
	v_cvt_pk_bf16_f32 v5, v8, v9
	s_add_u32 s0, s36, s0
	v_cvt_pk_bf16_f32 v85, v88, v89
	v_mfma_f32_32x32x16_bf16 v[98:113], v[160:163], v[170:173], v[98:113]
	s_nop 1
	v_cvt_pk_bf16_f32 v114, v114, v115
	v_cvt_pk_bf16_f32 v115, v116, v117
	v_cvt_pk_bf16_f32 v116, v118, v119
	v_cvt_pk_bf16_f32 v117, v120, v121
	ds_write2_b64 v86, v[66:67], v[68:69] offset0:72 offset1:74
	v_cvt_pk_bf16_f32 v66, v74, v75
	v_cvt_pk_bf16_f32 v67, v76, v77
	v_mfma_f32_32x32x16_bf16 v[18:33], v[156:159], v[182:185], v[18:33]
	s_nop 1
	v_cvt_pk_bf16_f32 v98, v98, v99
	v_cvt_pk_bf16_f32 v99, v100, v101
	v_cvt_pk_bf16_f32 v100, v102, v103
	v_cvt_pk_bf16_f32 v101, v104, v105
	v_cvt_pk_bf16_f32 v68, v78, v79
	v_cvt_pk_bf16_f32 v69, v80, v81
	ds_write2_b64 v34, v[2:3], v[4:5] offset0:8 offset1:10
	s_nop 2
	v_cvt_pk_bf16_f32 v18, v18, v19
	v_cvt_pk_bf16_f32 v19, v20, v21
	v_cvt_pk_bf16_f32 v20, v22, v23
	v_cvt_pk_bf16_f32 v21, v24, v25
	v_cvt_pk_bf16_f32 v2, v10, v11
	v_cvt_pk_bf16_f32 v3, v12, v13
	v_cvt_pk_bf16_f32 v4, v14, v15
	v_cvt_pk_bf16_f32 v5, v16, v17
	s_addc_u32 s1, s37, 0
	ds_write2_b64 v142, v[114:115], v[116:117] offset1:2
	v_cvt_pk_bf16_f32 v114, v122, v123
	v_cvt_pk_bf16_f32 v115, v124, v125
	v_cvt_pk_bf16_f32 v116, v126, v127
	v_cvt_pk_bf16_f32 v117, v128, v129
	ds_write2_b64 v142, v[98:99], v[100:101] offset0:8 offset1:10
	v_cvt_pk_bf16_f32 v98, v106, v107
	v_cvt_pk_bf16_f32 v99, v108, v109
	v_cvt_pk_bf16_f32 v100, v110, v111
	v_cvt_pk_bf16_f32 v101, v112, v113
	ds_write2_b64 v86, v[82:83], v[84:85] offset0:64 offset1:66
	v_cvt_pk_bf16_f32 v82, v90, v91
	v_cvt_pk_bf16_f32 v83, v92, v93
	v_cvt_pk_bf16_f32 v84, v94, v95
	v_cvt_pk_bf16_f32 v85, v96, v97
	ds_write2_b64 v86, v[66:67], v[68:69] offset0:76 offset1:78
	v_cvt_pk_bf16_f32 v51, v60, v61
	v_cvt_pk_bf16_f32 v52, v62, v63
	v_cvt_pk_bf16_f32 v53, v64, v65
	ds_write2_b64 v34, v[18:19], v[20:21] offset1:2
	v_cvt_pk_bf16_f32 v18, v26, v27
	v_cvt_pk_bf16_f32 v19, v28, v29
	v_cvt_pk_bf16_f32 v20, v30, v31
	v_cvt_pk_bf16_f32 v21, v32, v33
	ds_write2_b64 v34, v[2:3], v[4:5] offset0:12 offset1:14
	v_lshl_add_u64 v[2:3], s[0:1], 0, v[0:1]
	s_mov_b32 s0, 0
	ds_write2_b64 v142, v[114:115], v[116:117] offset0:4 offset1:6
	ds_write2_b64 v142, v[98:99], v[100:101] offset0:12 offset1:14
	ds_write2_b64 v86, v[82:83], v[84:85] offset0:68 offset1:70
	ds_write2_b64 v54, v[50:51], v[52:53] offset0:132 offset1:134
	ds_write2_b64 v34, v[18:19], v[20:21] offset0:4 offset1:6
	s_waitcnt lgkmcnt(0)
	s_barrier
